# G1 and G4: tiles beyond the first two per block handed out by per-XCD atomic counters (fetched one tile ahead, LDS mailbox), keeping the static order's XCD locality
# speedup vs baseline: 1.0921x; 1.0034x over previous
;   __device__ bool tile(long L, int& pm, int& pn) const {
;     if (L >= nwg) return false;
;     int wgid = (int)L; { const int q = nwg / NXCD, r = nwg % NXCD, xcd = wgid % NXCD, off = wgid / NXCD; wgid = (xcd < r ? xcd * (q + 1) : r * (q + 1) + (xcd - r) * q) + off; }
;     const int nig = WGM * nN, gid = wgid / nig, fm = gid * WGM, gsz = (nM - fm) < WGM ? (nM - fm) : WGM;
;     pm = fm + ((wgid % nig) % gsz); pn = (wgid % nig) / gsz; if (lat) pm = (pm >> 4) * 17 + 1 + (pm & 15); return true;
;   }
;     if (skipctx && (pm % 17) == 0 && pn >= 24) { u.nt = 4; u.split = 2; }
; template <class Epi, class Sched>
; __device__ __forceinline__ void gemm_phase(const int wv_, LAS unsigned char* lds, const int lda, const int ldb, const int K, const Sched& S, const Epi& E) {
;     ...
;     const bool has_next = S.next(ui + 1, nxt);
;     const char* nA = has_next ? nxt.a : cA; const char* nB = has_next ? nxt.b : cB;
.LBB0_203:
	s_add_i32 s41, s41, 1
	s_cmp_eq_u32 s33, 0x100
	s_cbranch_scc0 .Lg1d_static
	s_cmp_lt_u32 s41, 2
	s_cbranch_scc1 .Lg1d_first
	s_cmp_lg_u32 s72, 0
	s_cbranch_scc1 .Lg1d_wait
	s_waitcnt vmcnt(24)
	v_readfirstlane_b32 s10, v189
	v_mov_b32_e32 v240, 0x23ff8
	s_nop 1
	v_mov_b32_e32 v241, s10
	ds_write_b32 v240, v241
	s_load_dwordx2 s[6:7], s[0:1], 0x118
	v_readlane_b32 s12, v242, 59
	s_cmp_lg_u32 s12, 0
	s_cselect_b32 s12, 0x400, 0
	s_and_b32 s13, s2, 7
	s_lshl_b32 s13, s13, 7
	s_add_i32 s12, s12, s13
	s_waitcnt lgkmcnt(0)
	s_add_u32 s6, s6, 0x3a1e3800
	s_addc_u32 s7, s7, 0
	s_add_u32 s6, s6, s12
	s_addc_u32 s7, s7, 0
	v_mov_b32_e32 v241, 1
	s_mov_b64 s[12:13], exec
	s_mov_b64 exec, 1
	global_atomic_add v189, v2, v241, s[6:7] sc0
	s_mov_b64 exec, s[12:13]
	s_waitcnt lgkmcnt(0)
.Lg1d_wait:
	s_barrier
	v_mov_b32_e32 v240, 0x23ff8
	ds_read_b32 v241, v240
	s_waitcnt lgkmcnt(0)
	v_readfirstlane_b32 s20, v241
	s_mov_b32 s21, 0
	s_nop 1
	s_lshl_b32 s20, s20, 3
	s_and_b32 s10, s2, 7
	s_add_i32 s20, s20, s10
	s_add_i32 s20, s20, 0x200
	s_branch .Lg1d_have
.Lg1d_first:
	s_cmp_lg_u32 s72, 0
	s_cbranch_scc1 .Lg1d_static
	s_load_dwordx2 s[6:7], s[0:1], 0x118
	v_readlane_b32 s12, v242, 59
	s_cmp_lg_u32 s12, 0
	s_cselect_b32 s12, 0x400, 0
	s_and_b32 s13, s2, 7
	s_lshl_b32 s13, s13, 7
	s_add_i32 s12, s12, s13
	s_waitcnt lgkmcnt(0)
	s_add_u32 s6, s6, 0x3a1e3800
	s_addc_u32 s7, s7, 0
	s_add_u32 s6, s6, s12
	s_addc_u32 s7, s7, 0
	v_mov_b32_e32 v241, 1
	s_mov_b64 s[12:13], exec
	s_mov_b64 exec, 1
	global_atomic_add v189, v2, v241, s[6:7] sc0
	s_mov_b64 exec, s[12:13]
.Lg1d_static:
	s_mul_i32 s6, s41, s79
	s_mul_hi_u32 s7, s41, s33
	s_add_i32 s7, s7, s6
	s_mul_i32 s6, s41, s33
	s_add_u32 s20, s6, s2
	s_addc_u32 s21, s7, s44
.Lg1d_have:
	v_cmp_gt_i64_e64 s[6:7], s[20:21], v[154:155]
	s_and_b64 vcc, exec, s[6:7]
	s_cbranch_vccnz .LBB0_206
	s_ashr_i32 s10, s20, 31
	s_lshr_b32 s10, s10, 29
	s_add_i32 s10, s20, s10
	s_ashr_i32 s11, s10, 3
	s_and_b32 s10, s10, -8
	s_sub_i32 s10, s20, s10
	s_cmp_lt_i32 s10, 0
	s_cselect_b32 s12, s78, 0x1fe
	s_mul_i32 s10, s10, s12
	s_add_i32 s10, s10, s11
	s_mul_hi_i32 s11, s10, 0x88888889
	s_add_i32 s11, s11, s10
	s_lshr_b32 s12, s11, 31
	s_ashr_i32 s11, s11, 7
	s_add_i32 s11, s11, s12
	s_lshl_b32 s12, s11, 2
	s_sub_i32 s13, 0x44, s12
	s_min_i32 s13, s13, 4
	s_abs_i32 s14, s13
	v_cvt_f32_u32_e32 v4, s14
	s_sub_i32 s16, 0, s14
	s_mulk_i32 s11, 0xf0
	s_sub_i32 s11, s10, s11
	v_rcp_iflag_f32_e32 v4, v4
	s_abs_i32 s10, s11
	s_xor_b32 s15, s11, s13
	s_ashr_i32 s15, s15, 31
	v_mul_f32_e32 v4, 0x4f7ffffe, v4
	v_cvt_u32_f32_e32 v4, v4
	s_mov_b32 s42, 0
	v_readfirstlane_b32 s17, v4
	s_mul_i32 s16, s16, s17
	s_mul_hi_u32 s16, s17, s16
	s_add_i32 s17, s17, s16
	s_mul_hi_u32 s16, s10, s17
	s_mul_i32 s17, s16, s14
	s_sub_i32 s10, s10, s17
	s_add_i32 s17, s16, 1
	s_sub_i32 s20, s10, s14
	s_cmp_ge_u32 s10, s14
	s_cselect_b32 s16, s17, s16
	s_cselect_b32 s10, s20, s10
	s_add_i32 s17, s16, 1
	s_cmp_ge_u32 s10, s14
	s_cselect_b32 s10, s17, s16
	s_xor_b32 s10, s10, s15
	s_sub_i32 s10, s10, s15
	s_mul_i32 s13, s10, s13
	s_sub_i32 s11, s11, s13
	s_add_i32 s12, s12, s11
	s_ashr_i32 s13, s12, 31
	s_lshl_b64 s[14:15], s[12:13], 20
	s_add_u32 s14, s22, s14
	s_addc_u32 s15, s23, s15
	s_ashr_i32 s11, s10, 31
	s_lshl_b64 s[16:17], s[10:11], 20
	s_add_u32 s16, s24, s16
	s_addc_u32 s17, s25, s17
	s_andn2_b64 vcc, exec, s[68:69]
	s_mov_b32 s11, 32
	s_cbranch_vccnz .LBB0_206
	s_mul_i32 s11, s12, 0xf0f0f0f1
	s_add_i32 s11, s11, 0x7878787
	s_cmp_lt_u32 s11, 0xf0f0f0f
	s_cselect_b64 s[20:21], -1, 0
	s_cmp_gt_i32 s10, 23
	s_cselect_b64 s[50:51], -1, 0
	s_and_b64 s[20:21], s[50:51], s[20:21]
	s_and_b64 s[20:21], s[20:21], exec
	s_cselect_b32 s42, 2, 0
	s_cselect_b32 s11, 4, 32

;   __device__ bool tile(long L, int& pm, int& pn) const {
;     if (L >= nwg) return false;
;     int wgid = (int)L; { const int q = nwg / NXCD, r = nwg % NXCD, xcd = wgid % NXCD, off = wgid / NXCD; wgid = (xcd < r ? xcd * (q + 1) : r * (q + 1) + (xcd - r) * q) + off; }
;     const int nig = WGM * nN, gid = wgid / nig, fm = gid * WGM, gsz = (nM - fm) < WGM ? (nM - fm) : WGM;
;     pm = fm + ((wgid % nig) % gsz); pn = (wgid % nig) / gsz; if (lat) pm = (pm >> 4) * 17 + 1 + (pm & 15); return true;
;   }
;     if (skipctx && (pm % 17) == 0 && pn >= 24) { u.nt = 4; u.split = 2; }
; template <class Epi, class Sched>
; __device__ __forceinline__ void gemm_phase(const int wv_, LAS unsigned char* lds, const int lda, const int ldb, const int K, const Sched& S, const Epi& E) {
;     ...
;     const bool has_next = S.next(ui + 1, nxt);
;     const char* nA = has_next ? nxt.a : cA; const char* nB = has_next ? nxt.b : cB;
.LBB0_1168:
	s_add_i32 s47, s47, 1
	s_cmp_eq_u32 s33, 0x100
	s_cbranch_scc0 .Lg4d_static
	s_cmp_lt_u32 s47, 2
	s_cbranch_scc1 .Lg4d_first
	s_cmp_lg_u32 s72, 0
	s_cbranch_scc1 .Lg4d_wait
	s_waitcnt vmcnt(24)
	v_readfirstlane_b32 s13, v189
	v_mov_b32_e32 v240, 0x23ff8
	s_nop 1
	v_mov_b32_e32 v241, s13
	ds_write_b32 v240, v241
	s_load_dwordx2 s[8:9], s[0:1], 0x118
	v_readlane_b32 s12, v242, 59
	s_cmp_lg_u32 s12, 0
	s_cselect_b32 s12, 0x100, 0
	s_and_b32 s13, s2, 7
	s_lshl_b32 s13, s13, 5
	s_add_i32 s12, s12, s13
	s_waitcnt lgkmcnt(0)
	s_add_u32 s8, s8, 0x3a1e0000
	s_addc_u32 s9, s9, 0
	s_add_u32 s8, s8, s12
	s_addc_u32 s9, s9, 0
	v_mov_b32_e32 v241, 1
	s_mov_b64 s[12:13], exec
	s_mov_b64 exec, 1
	global_atomic_add v189, v2, v241, s[8:9] sc0
	s_mov_b64 exec, s[12:13]
	s_waitcnt lgkmcnt(0)
.Lg4d_wait:
	s_barrier
	v_mov_b32_e32 v240, 0x23ff8
	ds_read_b32 v241, v240
	s_waitcnt lgkmcnt(0)
	v_readfirstlane_b32 s30, v241
	s_mov_b32 s31, 0
	s_nop 1
	s_lshl_b32 s30, s30, 3
	s_and_b32 s13, s2, 7
	s_add_i32 s30, s30, s13
	s_add_i32 s30, s30, 0x200
	s_branch .Lg4d_have
.Lg4d_first:
	s_cmp_lg_u32 s72, 0
	s_cbranch_scc1 .Lg4d_static
	s_load_dwordx2 s[8:9], s[0:1], 0x118
	v_readlane_b32 s12, v242, 59
	s_cmp_lg_u32 s12, 0
	s_cselect_b32 s12, 0x100, 0
	s_and_b32 s13, s2, 7
	s_lshl_b32 s13, s13, 5
	s_add_i32 s12, s12, s13
	s_waitcnt lgkmcnt(0)
	s_add_u32 s8, s8, 0x3a1e0000
	s_addc_u32 s9, s9, 0
	s_add_u32 s8, s8, s12
	s_addc_u32 s9, s9, 0
	v_mov_b32_e32 v241, 1
	s_mov_b64 s[12:13], exec
	s_mov_b64 exec, 1
	global_atomic_add v189, v2, v241, s[8:9] sc0
	s_mov_b64 exec, s[12:13]
.Lg4d_static:
	s_mul_i32 s8, s47, s79
	s_mul_hi_u32 s9, s47, s33
	s_add_i32 s9, s9, s8
	s_mul_i32 s8, s47, s33
	s_add_u32 s30, s8, s2
	s_addc_u32 s31, s9, s44
.Lg4d_have:
	v_mov_b64_e32 v[4:5], s[86:87]
	v_cmp_ge_i64_e64 s[8:9], s[30:31], v[4:5]
	s_and_b64 vcc, exec, s[8:9]
	s_cbranch_vccnz .LBB0_1172
	s_ashr_i32 s12, s30, 31
	s_lshr_b32 s12, s12, 29
	s_add_i32 s12, s30, s12
	s_ashr_i32 s13, s12, 3
	s_and_b32 s12, s12, -8
	s_sub_i32 s12, s30, s12
	s_cmp_lt_i32 s12, 0
	s_cselect_b32 s16, s35, s34
	s_mul_i32 s12, s16, s12
	s_add_i32 s12, s12, s13
	s_ashr_i32 s13, s12, 31
	s_lshr_b32 s13, s13, 25
	s_add_i32 s13, s12, s13
	s_ashr_i32 s16, s13, 7
	s_lshl_b32 s16, s16, 2
	s_sub_i32 s17, s53, s16
	s_min_i32 s17, s17, 4
	s_abs_i32 s18, s17
	v_cvt_f32_u32_e32 v4, s18
	s_sub_i32 s20, 0, s18
	s_and_b32 s13, s13, 0xffffff80
	s_sub_i32 s13, s12, s13
	v_rcp_iflag_f32_e32 v4, v4
	s_abs_i32 s12, s13
	s_xor_b32 s19, s13, s17
	s_ashr_i32 s19, s19, 31
	v_mul_f32_e32 v4, 0x4f7ffffe, v4
	v_cvt_u32_f32_e32 v4, v4
	s_nop 0
	v_readfirstlane_b32 s21, v4
	s_mul_i32 s20, s20, s21
	s_mul_hi_u32 s20, s21, s20
	s_add_i32 s21, s21, s20
	s_mul_hi_u32 s20, s12, s21
	s_mul_i32 s21, s20, s18
	s_sub_i32 s12, s12, s21
	s_add_i32 s30, s20, 1
	s_sub_i32 s21, s12, s18
	s_cmp_ge_u32 s12, s18
	s_cselect_b32 s20, s30, s20
	s_cselect_b32 s12, s21, s12
	s_add_i32 s21, s20, 1
	s_cmp_ge_u32 s12, s18
	s_cselect_b32 s12, s21, s20
	s_xor_b32 s12, s12, s19
	s_sub_i32 s12, s12, s19
	s_mul_i32 s17, s12, s17
	s_sub_i32 s13, s13, s17
	s_and_b64 vcc, exec, s[4:5]
	s_add_i32 s16, s13, s16
	s_cbranch_vccnz .LBB0_1171
	s_ashr_i32 s13, s16, 4
	s_mul_i32 s13, s13, 17
	s_and_b32 s16, s16, 15
	s_add_i32 s13, s16, s13
	s_add_i32 s16, s13, 1
